# dense64 + MLA dense96 attention loops: softmax partial-sum adds done with v_pk_add_f32 accumulated across the four exp groups (17 instead of 32 VALU adds per tile)
# baseline (speedup 1.0000x reference)
.Lam96_exp:
	v_exp_f32_e32 v50, v50
	v_exp_f32_e32 v51, v51
	v_exp_f32_e32 v52, v52
	v_exp_f32_e32 v53, v53
	v_exp_f32_e32 v54, v54
	v_exp_f32_e32 v55, v55
	v_exp_f32_e32 v56, v56
	v_exp_f32_e32 v57, v57
	v_cvt_pk_bf16_f32 v196, v50, v51
	v_cvt_pk_bf16_f32 v197, v52, v53
	v_cvt_pk_bf16_f32 v198, v54, v55
	v_cvt_pk_bf16_f32 v199, v56, v57
	v_pk_add_f32 v[142:143], v[50:51], v[52:53]
	v_pk_add_f32 v[142:143], v[142:143], v[54:55]
	v_pk_add_f32 v[142:143], v[142:143], v[56:57]
	s_waitcnt lgkmcnt(10)
	v_mfma_f32_32x32x16_bf16 v[18:33], v[148:151], v[196:199], v[18:33]
	s_waitcnt lgkmcnt(8)
	v_mfma_f32_32x32x16_bf16 v[2:17], v[152:155], v[196:199], v[2:17]
	ds_read_b64_tr_b16 v[172:173], v144 offset:18432
	ds_read_b64_tr_b16 v[174:175], v144 offset:19456
	ds_read_b64_tr_b16 v[176:177], v145 offset:18432
	ds_read_b64_tr_b16 v[178:179], v145 offset:19456
	v_exp_f32_e32 v58, v58
	v_exp_f32_e32 v59, v59
	v_exp_f32_e32 v60, v60
	v_exp_f32_e32 v61, v61
	v_exp_f32_e32 v62, v62
	v_exp_f32_e32 v63, v63
	v_exp_f32_e32 v64, v64
	v_exp_f32_e32 v65, v65
	v_cvt_pk_bf16_f32 v200, v58, v59
	v_cvt_pk_bf16_f32 v201, v60, v61
	v_cvt_pk_bf16_f32 v202, v62, v63
	v_cvt_pk_bf16_f32 v203, v64, v65
	v_pk_add_f32 v[142:143], v[142:143], v[58:59]
	v_pk_add_f32 v[142:143], v[142:143], v[60:61]
	v_pk_add_f32 v[142:143], v[142:143], v[62:63]
	v_pk_add_f32 v[142:143], v[142:143], v[64:65]
	s_waitcnt lgkmcnt(10)
	v_mfma_f32_32x32x16_bf16 v[18:33], v[156:159], v[200:203], v[18:33]
	s_waitcnt lgkmcnt(8)
	v_mfma_f32_32x32x16_bf16 v[2:17], v[160:163], v[200:203], v[2:17]
	v_exp_f32_e32 v34, v34
	v_exp_f32_e32 v35, v35
	v_exp_f32_e32 v36, v36
	v_exp_f32_e32 v37, v37
	v_exp_f32_e32 v38, v38
	v_exp_f32_e32 v39, v39
	v_exp_f32_e32 v40, v40
	v_exp_f32_e32 v41, v41
	v_cvt_pk_bf16_f32 v204, v34, v35
	v_cvt_pk_bf16_f32 v205, v36, v37
	v_cvt_pk_bf16_f32 v206, v38, v39
	v_cvt_pk_bf16_f32 v207, v40, v41
	v_pk_add_f32 v[142:143], v[142:143], v[34:35]
	v_pk_add_f32 v[142:143], v[142:143], v[36:37]
	v_pk_add_f32 v[142:143], v[142:143], v[38:39]
	v_pk_add_f32 v[142:143], v[142:143], v[40:41]
	s_waitcnt lgkmcnt(6)
	v_mfma_f32_32x32x16_bf16 v[18:33], v[164:167], v[204:207], v[18:33]
	s_waitcnt lgkmcnt(4)
	v_mfma_f32_32x32x16_bf16 v[2:17], v[168:171], v[204:207], v[2:17]
	v_exp_f32_e32 v42, v42
	v_exp_f32_e32 v43, v43
	v_exp_f32_e32 v44, v44
	v_exp_f32_e32 v45, v45
	v_exp_f32_e32 v46, v46
	v_exp_f32_e32 v47, v47
	v_exp_f32_e32 v48, v48
	v_exp_f32_e32 v49, v49
	v_cvt_pk_bf16_f32 v232, v42, v43
	v_cvt_pk_bf16_f32 v233, v44, v45
	v_cvt_pk_bf16_f32 v234, v46, v47
	v_cvt_pk_bf16_f32 v235, v48, v49
	v_pk_add_f32 v[142:143], v[142:143], v[42:43]
	v_pk_add_f32 v[142:143], v[142:143], v[44:45]
	v_pk_add_f32 v[142:143], v[142:143], v[46:47]
	v_pk_add_f32 v[142:143], v[142:143], v[48:49]
	v_add_f32_e32 v131, v131, v142
	v_add_f32_e32 v131, v131, v143
	s_waitcnt lgkmcnt(2)
	v_mfma_f32_32x32x16_bf16 v[18:33], v[172:175], v[232:235], v[18:33]
	s_waitcnt lgkmcnt(0)
	v_mfma_f32_32x32x16_bf16 v[2:17], v[176:179], v[232:235], v[2:17]
	s_bitcmp1_b32 s25, 0
	s_cselect_b32 s26, 0x5000, 0
	v_add3_u32 v138, s26, v119, v118
	v_add3_u32 v139, s26, v121, v120
	v_add3_u32 v140, s26, v122, v123
	s_waitcnt vmcnt(1)
	ds_write_b128 v138, v[94:97]
	s_and_b64 s[48:49], exec, s[38:39]
	s_cbranch_scc0 .Lam96_nos2
	ds_write_b128 v139, v[90:93]
	v_lshl_add_u64 v[242:243], v[242:243], 0, v[208:209]

.Lad64_exp:
	v_exp_f32_e32 v34, v34
	v_exp_f32_e32 v35, v35
	v_exp_f32_e32 v36, v36
	v_exp_f32_e32 v37, v37
	v_exp_f32_e32 v38, v38
	v_exp_f32_e32 v39, v39
	v_exp_f32_e32 v40, v40
	v_exp_f32_e32 v41, v41
	v_cvt_pk_bf16_f32 v220, v34, v35
	v_cvt_pk_bf16_f32 v221, v36, v37
	v_cvt_pk_bf16_f32 v222, v38, v39
	v_cvt_pk_bf16_f32 v223, v40, v41
	v_pk_add_f32 v[208:209], v[34:35], v[36:37]
	v_pk_add_f32 v[208:209], v[208:209], v[38:39]
	v_pk_add_f32 v[208:209], v[208:209], v[40:41]
	s_waitcnt lgkmcnt(10)
	v_mfma_f32_32x32x16_bf16 v[18:33], v[180:183], v[220:223], v[18:33]
	s_waitcnt lgkmcnt(8)
	v_mfma_f32_32x32x16_bf16 v[2:17], v[184:187], v[220:223], v[2:17]
	ds_read_b64_tr_b16 v[204:205], v134 offset:14336
	ds_read_b64_tr_b16 v[206:207], v134 offset:15360
	ds_read_b64_tr_b16 v[216:217], v117 offset:14336
	ds_read_b64_tr_b16 v[218:219], v117 offset:15360
	v_exp_f32_e32 v42, v42
	v_exp_f32_e32 v43, v43
	v_exp_f32_e32 v44, v44
	v_exp_f32_e32 v45, v45
	v_exp_f32_e32 v46, v46
	v_exp_f32_e32 v47, v47
	v_exp_f32_e32 v48, v48
	v_exp_f32_e32 v49, v49
	v_cvt_pk_bf16_f32 v224, v42, v43
	v_cvt_pk_bf16_f32 v225, v44, v45
	v_cvt_pk_bf16_f32 v226, v46, v47
	v_cvt_pk_bf16_f32 v227, v48, v49
	v_pk_add_f32 v[208:209], v[208:209], v[42:43]
	v_pk_add_f32 v[208:209], v[208:209], v[44:45]
	v_pk_add_f32 v[208:209], v[208:209], v[46:47]
	v_pk_add_f32 v[208:209], v[208:209], v[48:49]
	s_waitcnt lgkmcnt(10)
	v_mfma_f32_32x32x16_bf16 v[18:33], v[188:191], v[224:227], v[18:33]
	s_waitcnt lgkmcnt(8)
	v_mfma_f32_32x32x16_bf16 v[2:17], v[192:195], v[224:227], v[2:17]
	v_exp_f32_e32 v50, v50
	v_exp_f32_e32 v51, v51
	v_exp_f32_e32 v52, v52
	v_exp_f32_e32 v53, v53
	v_exp_f32_e32 v54, v54
	v_exp_f32_e32 v55, v55
	v_exp_f32_e32 v56, v56
	v_exp_f32_e32 v57, v57
	v_cvt_pk_bf16_f32 v228, v50, v51
	v_cvt_pk_bf16_f32 v229, v52, v53
	v_cvt_pk_bf16_f32 v230, v54, v55
	v_cvt_pk_bf16_f32 v231, v56, v57
	v_pk_add_f32 v[208:209], v[208:209], v[50:51]
	v_pk_add_f32 v[208:209], v[208:209], v[52:53]
	v_pk_add_f32 v[208:209], v[208:209], v[54:55]
	v_pk_add_f32 v[208:209], v[208:209], v[56:57]
	s_waitcnt lgkmcnt(6)
	v_mfma_f32_32x32x16_bf16 v[18:33], v[196:199], v[228:231], v[18:33]
	s_waitcnt lgkmcnt(4)
	v_mfma_f32_32x32x16_bf16 v[2:17], v[200:203], v[228:231], v[2:17]
	v_exp_f32_e32 v58, v58
	v_exp_f32_e32 v59, v59
	v_exp_f32_e32 v60, v60
	v_exp_f32_e32 v61, v61
	v_exp_f32_e32 v62, v62
	v_exp_f32_e32 v63, v63
	v_exp_f32_e32 v64, v64
	v_exp_f32_e32 v65, v65
	v_cvt_pk_bf16_f32 v232, v58, v59
	v_cvt_pk_bf16_f32 v233, v60, v61
	v_cvt_pk_bf16_f32 v234, v62, v63
	v_cvt_pk_bf16_f32 v235, v64, v65
	v_pk_add_f32 v[208:209], v[208:209], v[58:59]
	v_pk_add_f32 v[208:209], v[208:209], v[60:61]
	v_pk_add_f32 v[208:209], v[208:209], v[62:63]
	v_pk_add_f32 v[208:209], v[208:209], v[64:65]
	v_add_f32_e32 v96, v96, v208
	v_add_f32_e32 v96, v96, v209
	s_waitcnt lgkmcnt(2)
	v_mfma_f32_32x32x16_bf16 v[18:33], v[204:207], v[232:235], v[18:33]
	s_waitcnt lgkmcnt(0)
	v_mfma_f32_32x32x16_bf16 v[2:17], v[216:219], v[232:235], v[2:17]
	s_and_b32 s26, s24, 0x4000
	v_add3_u32 v134, s26, v106, v101
	v_add3_u32 v117, s26, v97, v99
	s_waitcnt vmcnt(1)
	ds_write_b128 v134, v[82:85]
	s_waitcnt vmcnt(0)
	ds_write_b128 v117, v[86:89] offset:8192
	s_add_i32 s10, s10, 1
	s_addk_i32 s24, 0x4000
	s_mov_b32 s25, s26
	v_add_u32_e32 v134, s25, v98
	v_add_u32_e32 v117, s25, v109
	v_add_u32_e32 v208, s25, v111
	v_add_u32_e32 v209, s25, v114
	v_lshl_add_u64 v[240:241], v[240:241], 0, v[244:245]
	v_lshl_add_u64 v[242:243], v[242:243], 0, v[244:245]
	s_cmp_lg_u32 s10, 39
	s_waitcnt lgkmcnt(0)
	s_barrier
	s_cbranch_scc1 .Lad64_top
	s_setprio 0
	s_branch .LBB0_345
